# same as v38 without the static s_setprio for waves 4-7
# speedup vs baseline: 1.0469x; 1.0029x over previous
; #define LAS __attribute__((address_space(3)))
; template <int D1, int D2, int DV>
; DI void attn_core(f32x16 (&o)[DV / 32], float& l_out, LAS unsigned char* lds, const bf16_t* q1, const bf16_t* q2,
;                   const bf16_t* k1, long ldk1, const bf16_t* k2, long ldk2, const bf16_t* vt, long ldv, int ntiles) {
;     ...
;     gload(0); sstore(0); if (ntiles > 1) { gload(1); sstore(1); } __syncthreads();
;     for (int t = 0; t < ntiles; ++t) {
;         if (t + 2 < ntiles) gload(t + 2);
;         const LAS unsigned char* kb = lds + (t & 3) * BUF; const LAS unsigned char* vb = kb + KT;
;         f32x16 p[2];
;         {
;             bf16x8 kf[2][DQK / 16];
; #pragma unroll
;             for (int hf = 0; hf < 2; ++hf)
; #pragma unroll
;                 for (int d0 = 0; d0 < DQK / 16; ++d0) kf[hf][d0] = *(const LAS bf16x8*)(kb + (32 * hf + pr) * KROW + (16 * d0 + 8 * h) * 2);
;             __builtin_amdgcn_sched_barrier(0);
;             __builtin_amdgcn_s_setprio(2);
; #pragma unroll
;             for (int d0 = 0; d0 < DQK / 16; ++d0)
; #pragma unroll
;                 for (int hf = 0; hf < 2; ++hf) p[hf] = MFMA32(kf[hf][d0], qf[d0], d0 == 0 ? negm : p[hf]);
;             __builtin_amdgcn_sched_barrier(0);
;         }
;         constexpr int NBLK = DV / 32;
;         bf16x8 vk[2][NBLK];
;     ...
;         LDVK(0, 0);
;         __builtin_amdgcn_sched_barrier(0);
;         float ta = fmaxf(fmaxf(p[0][0], p[0][1]), p[1][0]), tb = fmaxf(fmaxf(p[0][2], p[0][3]), p[1][1]);
;         ta = fmaxf(fmaxf(ta, p[1][2]), p[1][3]);
; #pragma unroll
;         for (int i = 4; i < 16; i += 4) { ta = fmaxf(fmaxf(ta, p[0][i]), p[0][i + 1]); tb = fmaxf(fmaxf(tb, p[0][i + 2]), p[0][i + 3]); ta = fmaxf(fmaxf(ta, p[1][i]), p[1][i + 1]); tb = fmaxf(fmaxf(tb, p[1][i + 2]), p[1][i + 3]); }
;         float tm = fmaxf(ta, tb);
;         if (__any(t == 0 || tm > 8.0f)) {
;             tm = fmaxf(tm, __shfl_xor(tm, 32));
;             const float dl = (t == 0 || tm > 0.f) ? tm : 0.f; mrun += dl;
;             const float alpha = __builtin_amdgcn_exp2f(-dl); lrun *= alpha;
; #pragma unroll
;             for (int i = 0; i < 16; ++i) { p[0][i] -= dl; p[1][i] -= dl; negm[i] = -mrun; }
; #pragma unroll
;             for (int b = 0; b < DV / 32; ++b)
; #pragma unroll
;                 for (int i = 0; i < 16; ++i) o[b][i] *= alpha;
;         }
;         bf16x8 pf[4]; float rs = 0.f; u32x4 wq;
.LBB0_207:
	s_or_b64 exec, exec, s[0:1]
	v_mul_u32_u24_e32 v200, 0x90, v1
	v_add_f32_e32 v1, 0, v96
	v_add_f32_e32 v1, v97, v1
	v_add_f32_e32 v1, v98, v1
	v_add_f32_e32 v1, v99, v1
	v_add_f32_e32 v1, v100, v1
	v_add_f32_e32 v1, v101, v1
	v_add_f32_e32 v1, v102, v1
	v_add_f32_e32 v1, v103, v1
	v_add_f32_e32 v1, v104, v1
	v_add_f32_e32 v1, v105, v1
	v_add_f32_e32 v1, v106, v1
	v_add_f32_e32 v1, v107, v1
	v_add_f32_e32 v1, v108, v1
	v_add_f32_e32 v1, v109, v1
	v_add_f32_e32 v1, v110, v1
	v_add_f32_e32 v1, v111, v1
	v_add_f32_e32 v1, v3, v1
	v_add_f32_e32 v1, v4, v1
	v_add_f32_e32 v1, v5, v1
	v_add_f32_e32 v1, v6, v1
	v_add_f32_e32 v1, v7, v1
	v_add_f32_e32 v1, v8, v1
	v_add_f32_e32 v1, v9, v1
	v_add_f32_e32 v1, v10, v1
	v_add_f32_e32 v1, v11, v1
	v_mad_i64_i32 v[84:85], s[0:1], v151, s7, 0
	v_mad_i64_i32 v[86:87], s[0:1], v152, s7, 0
	v_add_f32_e32 v1, v12, v1
	v_add_f32_e32 v1, v13, v1
	s_lshl_b32 s0, s4, 7
	v_add_f32_e32 v1, v14, v1
	s_and_b32 s0, s0, 0x200
	s_lshl_b32 s1, s6, 7
	v_add_f32_e32 v1, v15, v1
	s_add_i32 s0, s0, s1
	v_add_f32_e32 v1, v80, v1
	s_bfe_u32 s7, s0, 0x30007
	v_add_f32_e32 v1, v81, v1
	s_lshl_b32 s6, s7, 8
	v_add_f32_e32 v1, v82, v1
	s_add_u32 s0, s6, s28
	v_add_f32_e32 v201, v2, v1
	v_lshlrev_b64 v[2:3], 12, v[146:147]
	s_addc_u32 s1, 0, s29
	v_lshl_add_u64 v[2:3], s[0:1], 0, v[2:3]
	v_readlane_b32 s0, v243, 52
	v_lshl_add_u64 v[2:3], v[148:149], 1, v[2:3]
	v_readlane_b32 s1, v243, 53
	s_waitcnt vmcnt(1)
	ds_write_b128 v145, v[132:135] offset:64512
	s_waitcnt vmcnt(0)
	ds_write_b128 v150, v[136:139] offset:64512
	v_lshl_add_u64 v[162:163], s[0:1], 0, v[2:3]
	v_mad_u64_u32 v[2:3], s[0:1], s7, v187, v[84:85]
	v_mov_b32_e32 v145, v157
	s_add_u32 s0, s10, s42
	v_readlane_b32 s1, v243, 59
	v_lshl_add_u64 v[2:3], v[2:3], 0, v[144:145]
	s_addc_u32 s1, s1, s43
	v_lshl_add_u64 v[164:165], s[0:1], 0, v[2:3]
	v_mad_u64_u32 v[2:3], s[8:9], s7, v187, v[86:87]
	v_lshl_add_u64 v[2:3], v[2:3], 0, v[144:145]
	s_mul_i32 s44, s7, 0x840000
	s_mov_b32 s45, s24
	v_lshl_add_u64 v[166:167], s[0:1], 0, v[2:3]
	s_mov_b32 s7, 3
	v_mov_b32_e32 v1, v0
	v_mov_b32_e32 v2, v0
	v_mov_b32_e32 v3, v0
	v_mov_b32_e32 v4, v0
	v_mov_b32_e32 v5, v0
	v_mov_b32_e32 v6, v0
	v_mov_b32_e32 v7, v0
	v_mov_b32_e32 v8, v0
	v_mov_b32_e32 v9, v0
	v_mov_b32_e32 v10, v0
	v_mov_b32_e32 v11, v0
	v_mov_b32_e32 v12, v0
	v_mov_b32_e32 v13, v0
	v_mov_b32_e32 v14, v0
	v_mov_b32_e32 v15, v0
	global_load_dwordx4 v[128:131], v[162:163], off
	global_load_dwordx4 v[132:135], v[164:165], off
	global_load_dwordx4 v[136:139], v[166:167], off
	s_mov_b64 s[0:1], 0x40000
	v_lshl_add_u64 v[162:163], v[162:163], 0, s[0:1]
	s_mov_b64 s[0:1], 0x80
	v_lshl_add_u64 v[164:165], v[164:165], 0, s[0:1]
	v_lshl_add_u64 v[166:167], v[166:167], 0, s[0:1]
	v_readfirstlane_b32 s0, v162
	v_readfirstlane_b32 s1, v163
	s_nop 3
	v_subrev_u32_e32 v162, s0, v162
	v_subrev_u32_e32 v164, s0, v164
	v_subrev_u32_e32 v166, s0, v166
	s_waitcnt lgkmcnt(0)
	s_mov_b32 s7, 1
	s_movk_i32 s9, 0x6c00
	v_add3_u32 v247, s9, v200, v197
	ds_read_b128 v[140:143], v247 offset:0
	ds_read_b128 v[144:147], v247 offset:32
	ds_read_b128 v[148:151], v247 offset:64
	ds_read_b128 v[152:155], v247 offset:96
	v_add3_u32 v246, s9, v199, v197
	s_waitcnt lgkmcnt(2)
	v_mfma_f32_32x32x16_bf16 v[96:111], v[140:143], v[112:115], v[0:15]
	ds_read_b128 v[140:143], v247 offset:4608
	v_mfma_f32_32x32x16_bf16 v[96:111], v[144:147], v[116:119], v[96:111]
	ds_read_b128 v[144:147], v247 offset:4640
	s_waitcnt lgkmcnt(2)
	v_mfma_f32_32x32x16_bf16 v[96:111], v[148:151], v[120:123], v[96:111]
	ds_read_b128 v[148:151], v247 offset:4672
	v_mfma_f32_32x32x16_bf16 v[96:111], v[152:155], v[124:127], v[96:111]
	ds_read_b128 v[152:155], v247 offset:4704
	s_waitcnt lgkmcnt(2)
	v_mfma_f32_32x32x16_bf16 v[80:95], v[140:143], v[112:115], v[0:15]
	ds_read_b128 v[208:211], v246 offset:9216
	v_mfma_f32_32x32x16_bf16 v[80:95], v[144:147], v[116:119], v[80:95]
	ds_read_b128 v[212:215], v246 offset:13824
	s_waitcnt lgkmcnt(2)
	v_mfma_f32_32x32x16_bf16 v[80:95], v[148:151], v[120:123], v[80:95]
	ds_read_b128 v[216:219], v246 offset:18432
	v_mfma_f32_32x32x16_bf16 v[80:95], v[152:155], v[124:127], v[80:95]
	ds_read_b128 v[220:223], v246 offset:23040
	s_nop 15
	v_exp_f32_e32 v232, v96
	v_exp_f32_e32 v233, v97
	s_nop 0
	v_cvt_pk_bf16_f32 v224, v232, v233
	v_exp_f32_e32 v234, v98
	v_exp_f32_e32 v235, v99
	s_nop 0
	v_cvt_pk_bf16_f32 v225, v234, v235
	v_exp_f32_e32 v236, v100
	v_exp_f32_e32 v237, v101
	s_nop 0
	v_cvt_pk_bf16_f32 v226, v236, v237
	v_exp_f32_e32 v238, v102
	v_exp_f32_e32 v239, v103
	s_nop 0
	v_cvt_pk_bf16_f32 v227, v238, v239
	s_mov_b32 s26, 0x14400
	s_waitcnt vmcnt(0)
	v_add3_u32 v247, s26, v195, v196
	ds_write_b128 v247, v[128:131] offset:0
	v_add3_u32 v247, s26, v193, v156
	ds_write_b128 v247, v[132:135] offset:9216
	v_add3_u32 v247, s26, v194, v156
	ds_write_b128 v247, v[136:139] offset:9216
	s_mov_b32 s8, 0x6c00
	s_mov_b32 s9, 0xd800
	s_mov_b32 s26, 0x1b000
	s_mov_b32 s27, 0x14400
	s_nop 1

; #define LAS __attribute__((address_space(3)))
; template <int D1, int D2, int DV>
; DI void attn_core(f32x16 (&o)[DV / 32], float& l_out, LAS unsigned char* lds, const bf16_t* q1, const bf16_t* q2,
;                   const bf16_t* k1, long ldk1, const bf16_t* k2, long ldk2, const bf16_t* vt, long ldv, int ntiles) {
;     ...
;     gload(0); sstore(0); if (ntiles > 1) { gload(1); sstore(1); } __syncthreads();
;     for (int t = 0; t < ntiles; ++t) {
;         if (t + 2 < ntiles) gload(t + 2);
;         const LAS unsigned char* kb = lds + (t & 3) * BUF; const LAS unsigned char* vb = kb + KT;
;         f32x16 p[2];
;         {
;             bf16x8 kf[2][DQK / 16];
; #pragma unroll
;             for (int hf = 0; hf < 2; ++hf)
; #pragma unroll
;                 for (int d0 = 0; d0 < DQK / 16; ++d0) kf[hf][d0] = *(const LAS bf16x8*)(kb + (32 * hf + pr) * KROW + (16 * d0 + 8 * h) * 2);
;             __builtin_amdgcn_sched_barrier(0);
;             __builtin_amdgcn_s_setprio(2);
; #pragma unroll
;             for (int d0 = 0; d0 < DQK / 16; ++d0)
; #pragma unroll
;                 for (int hf = 0; hf < 2; ++hf) p[hf] = MFMA32(kf[hf][d0], qf[d0], d0 == 0 ? negm : p[hf]);
;             __builtin_amdgcn_sched_barrier(0);
;         }
;         constexpr int NBLK = DV / 32;
;         bf16x8 vk[2][NBLK];
;     ...
;         LDVK(0, 0);
;         __builtin_amdgcn_sched_barrier(0);
;         float ta = fmaxf(fmaxf(p[0][0], p[0][1]), p[1][0]), tb = fmaxf(fmaxf(p[0][2], p[0][3]), p[1][1]);
;         ta = fmaxf(fmaxf(ta, p[1][2]), p[1][3]);
; #pragma unroll
;         for (int i = 4; i < 16; i += 4) { ta = fmaxf(fmaxf(ta, p[0][i]), p[0][i + 1]); tb = fmaxf(fmaxf(tb, p[0][i + 2]), p[0][i + 3]); ta = fmaxf(fmaxf(ta, p[1][i]), p[1][i + 1]); tb = fmaxf(fmaxf(tb, p[1][i + 2]), p[1][i + 3]); }
;         float tm = fmaxf(ta, tb);
;         if (__any(t == 0 || tm > 8.0f)) {
;             tm = fmaxf(tm, __shfl_xor(tm, 32));
;             const float dl = (t == 0 || tm > 0.f) ? tm : 0.f; mrun += dl;
;             const float alpha = __builtin_amdgcn_exp2f(-dl); lrun *= alpha;
; #pragma unroll
;             for (int i = 0; i < 16; ++i) { p[0][i] -= dl; p[1][i] -= dl; negm[i] = -mrun; }
; #pragma unroll
;             for (int b = 0; b < DV / 32; ++b)
; #pragma unroll
;                 for (int i = 0; i < 16; ++i) o[b][i] *= alpha;
;         }
;         bf16x8 pf[4]; float rs = 0.f; u32x4 wq;
.LBB0_238:
	s_or_b64 exec, exec, s[0:1]
	v_add_f32_e32 v83, 0, v111
	v_add_f32_e32 v83, v140, v83
	v_add_f32_e32 v83, v141, v83
	v_add_f32_e32 v83, v142, v83
	v_add_f32_e32 v83, v143, v83
	v_add_f32_e32 v83, v144, v83
	v_add_f32_e32 v83, v145, v83
	v_add_f32_e32 v83, v146, v83
	v_add_f32_e32 v83, v147, v83
	v_add_f32_e32 v83, v148, v83
	v_add_f32_e32 v83, v149, v83
	v_add_f32_e32 v83, v150, v83
	v_add_f32_e32 v83, v151, v83
	v_add_f32_e32 v83, v152, v83
	v_add_f32_e32 v83, v153, v83
	v_add_f32_e32 v83, v154, v83
	v_add_f32_e32 v66, v66, v83
	v_add_f32_e32 v66, v67, v66
	v_add_f32_e32 v66, v68, v66
	v_add_f32_e32 v66, v69, v66
	v_add_f32_e32 v66, v70, v66
	v_add_f32_e32 v66, v71, v66
	v_add_f32_e32 v66, v72, v66
	v_add_f32_e32 v66, v73, v66
	v_add_f32_e32 v66, v74, v66
	v_add_f32_e32 v66, v75, v66
	v_add_f32_e32 v66, v76, v66
	v_add_f32_e32 v66, v77, v66
	v_add_f32_e32 v66, v78, v66
	v_add_f32_e32 v66, v79, v66
	v_mad_i64_i32 v[84:85], s[0:1], v108, s7, 0
	v_mad_i64_i32 v[86:87], s[0:1], v109, s7, 0
	v_add_f32_e32 v66, v80, v66
	v_add_f32_e32 v66, v81, v66
	s_add_u32 s0, s6, s28
	v_add_f32_e32 v199, v82, v66
	v_lshlrev_b64 v[66:67], 12, v[104:105]
	s_addc_u32 s1, 0, s29
	v_lshl_add_u64 v[66:67], s[0:1], 0, v[66:67]
	v_readlane_b32 s0, v243, 60
	v_lshl_add_u64 v[66:67], v[106:107], 1, v[66:67]
	v_readlane_b32 s1, v243, 61
	s_waitcnt vmcnt(1)
	ds_write_b128 v65, v[132:135] offset:64512
	s_waitcnt vmcnt(0)
	ds_write_b128 v103, v[136:139] offset:64512
	v_lshl_add_u64 v[160:161], s[0:1], 0, v[66:67]
	v_lshl_add_u64 v[66:67], s[44:45], 0, v[84:85]
	v_mov_b32_e32 v103, v157
	s_add_u32 s0, s10, s42
	v_readlane_b32 s1, v243, 59
	v_lshl_add_u64 v[66:67], v[66:67], 0, v[102:103]
	s_addc_u32 s1, s1, s43
	v_lshl_add_u64 v[162:163], s[0:1], 0, v[66:67]
	v_lshl_add_u64 v[66:67], s[44:45], 0, v[86:87]
	v_lshl_add_u64 v[66:67], v[66:67], 0, v[102:103]
	v_mul_u32_u24_e32 v198, 0x90, v110
	v_lshl_add_u64 v[164:165], s[0:1], 0, v[66:67]
	s_mov_b32 s6, 3
	v_mov_b32_e32 v65, v64
	v_mov_b32_e32 v66, v64
	v_mov_b32_e32 v67, v64
	v_mov_b32_e32 v68, v64
	v_mov_b32_e32 v69, v64
	v_mov_b32_e32 v70, v64
	v_mov_b32_e32 v71, v64
	v_mov_b32_e32 v72, v64
	v_mov_b32_e32 v73, v64
	v_mov_b32_e32 v74, v64
	v_mov_b32_e32 v75, v64
	v_mov_b32_e32 v76, v64
	v_mov_b32_e32 v77, v64
	v_mov_b32_e32 v78, v64
	v_mov_b32_e32 v79, v64
	global_load_dwordx4 v[128:131], v[160:161], off
	global_load_dwordx4 v[132:135], v[162:163], off
	global_load_dwordx4 v[136:139], v[164:165], off
	s_mov_b64 s[0:1], 0x40000
	v_lshl_add_u64 v[160:161], v[160:161], 0, s[0:1]
	s_mov_b64 s[0:1], 0x80
	v_lshl_add_u64 v[162:163], v[162:163], 0, s[0:1]
	v_lshl_add_u64 v[164:165], v[164:165], 0, s[0:1]
	v_readfirstlane_b32 s0, v160
	v_readfirstlane_b32 s1, v161
	s_nop 3
	v_subrev_u32_e32 v160, s0, v160
	v_subrev_u32_e32 v162, s0, v162
	v_subrev_u32_e32 v164, s0, v164
	s_waitcnt lgkmcnt(0)
	s_mov_b32 s7, 1
	s_movk_i32 s9, 0x6c00
	v_add3_u32 v247, s9, v198, v195
	ds_read_b128 v[140:143], v247 offset:0
	ds_read_b128 v[144:147], v247 offset:32
	ds_read_b128 v[148:151], v247 offset:64
	ds_read_b128 v[152:155], v247 offset:96
	v_add3_u32 v246, s9, v197, v195
	s_waitcnt lgkmcnt(2)
	v_mfma_f32_32x32x16_bf16 v[96:111], v[140:143], v[112:115], v[64:79]
	ds_read_b128 v[140:143], v247 offset:4608
	v_mfma_f32_32x32x16_bf16 v[96:111], v[144:147], v[116:119], v[96:111]
	ds_read_b128 v[144:147], v247 offset:4640
	s_waitcnt lgkmcnt(2)
	v_mfma_f32_32x32x16_bf16 v[96:111], v[148:151], v[120:123], v[96:111]
	ds_read_b128 v[148:151], v247 offset:4672
	v_mfma_f32_32x32x16_bf16 v[96:111], v[152:155], v[124:127], v[96:111]
	ds_read_b128 v[152:155], v247 offset:4704
	s_waitcnt lgkmcnt(2)
	v_mfma_f32_32x32x16_bf16 v[80:95], v[140:143], v[112:115], v[64:79]
	ds_read_b128 v[208:211], v246 offset:9216
	v_mfma_f32_32x32x16_bf16 v[80:95], v[144:147], v[116:119], v[80:95]
	ds_read_b128 v[212:215], v246 offset:13824
	s_waitcnt lgkmcnt(2)
	v_mfma_f32_32x32x16_bf16 v[80:95], v[148:151], v[120:123], v[80:95]
	ds_read_b128 v[216:219], v246 offset:18432
	v_mfma_f32_32x32x16_bf16 v[80:95], v[152:155], v[124:127], v[80:95]
	ds_read_b128 v[220:223], v246 offset:23040
	s_nop 15
	v_exp_f32_e32 v232, v96
	v_exp_f32_e32 v233, v97
	s_nop 0
	v_cvt_pk_bf16_f32 v224, v232, v233
	v_exp_f32_e32 v234, v98
	v_exp_f32_e32 v235, v99
	s_nop 0
	v_cvt_pk_bf16_f32 v225, v234, v235
	v_exp_f32_e32 v236, v100
	v_exp_f32_e32 v237, v101
	s_nop 0
	v_cvt_pk_bf16_f32 v226, v236, v237
	v_exp_f32_e32 v238, v102
	v_exp_f32_e32 v239, v103
	s_nop 0
	v_cvt_pk_bf16_f32 v227, v238, v239
	s_mov_b32 s26, 0x14400
	s_waitcnt vmcnt(0)
	v_add3_u32 v247, s26, v193, v194
	ds_write_b128 v247, v[128:131] offset:0
	v_add3_u32 v247, s26, v167, v156
	ds_write_b128 v247, v[132:135] offset:9216
	v_add3_u32 v247, s26, v192, v156
	ds_write_b128 v247, v[136:139] offset:9216
	s_mov_b32 s8, 0x6c00
	s_mov_b32 s9, 0xd800
	s_mov_b32 s26, 0x1b000
	s_mov_b32 s27, 0x14400
	s_nop 1

; #define LAS __attribute__((address_space(3)))
; template <int D1, int D2, int DV>
; DI void attn_core(f32x16 (&o)[DV / 32], float& l_out, LAS unsigned char* lds, const bf16_t* q1, const bf16_t* q2,
;                   const bf16_t* k1, long ldk1, const bf16_t* k2, long ldk2, const bf16_t* vt, long ldv, int ntiles) {
;     ...
;     const int pr = (r & ~12) | ((r & 4) << 1) | ((r & 8) >> 1);
;     float mrun = 0.f, lrun = 0.f;
;     f32x16 negm;
; #pragma unroll
;     for (int i = 0; i < 16; ++i) negm[i] = 0.f;
; #pragma unroll
;     for (int b = 0; b < DV / 32; ++b)
; #pragma unroll
;         for (int i = 0; i < 16; ++i) o[b][i] = 0.f;
;     gload(0); sstore(0); if (ntiles > 1) { gload(1); sstore(1); } __syncthreads();
;     for (int t = 0; t < ntiles; ++t) {
;         if (t + 2 < ntiles) gload(t + 2);
;         const LAS unsigned char* kb = lds + (t & 3) * BUF; const LAS unsigned char* vb = kb + KT;
;         f32x16 p[2];
;         {
;             bf16x8 kf[2][DQK / 16];
; #pragma unroll
;             for (int hf = 0; hf < 2; ++hf)
; #pragma unroll
;                 for (int d0 = 0; d0 < DQK / 16; ++d0) kf[hf][d0] = *(const LAS bf16x8*)(kb + (32 * hf + pr) * KROW + (16 * d0 + 8 * h) * 2);
;             __builtin_amdgcn_sched_barrier(0);
;             __builtin_amdgcn_s_setprio(2);
; #pragma unroll
;             for (int d0 = 0; d0 < DQK / 16; ++d0)
; #pragma unroll
;                 for (int hf = 0; hf < 2; ++hf) p[hf] = MFMA32(kf[hf][d0], qf[d0], d0 == 0 ? negm : p[hf]);
;             __builtin_amdgcn_sched_barrier(0);
;         }
;         constexpr int NBLK = DV / 32;
;         bf16x8 vk[2][NBLK];
;     ...
;         LDVK(0, 0);
;         __builtin_amdgcn_sched_barrier(0);
;         float ta = fmaxf(fmaxf(p[0][0], p[0][1]), p[1][0]), tb = fmaxf(fmaxf(p[0][2], p[0][3]), p[1][1]);
;         ta = fmaxf(fmaxf(ta, p[1][2]), p[1][3]);
; #pragma unroll
;         for (int i = 4; i < 16; i += 4) { ta = fmaxf(fmaxf(ta, p[0][i]), p[0][i + 1]); tb = fmaxf(fmaxf(tb, p[0][i + 2]), p[0][i + 3]); ta = fmaxf(fmaxf(ta, p[1][i]), p[1][i + 1]); tb = fmaxf(fmaxf(tb, p[1][i + 2]), p[1][i + 3]); }
;         float tm = fmaxf(ta, tb);
;         if (__any(t == 0 || tm > 8.0f)) {
;             tm = fmaxf(tm, __shfl_xor(tm, 32));
;             const float dl = (t == 0 || tm > 0.f) ? tm : 0.f; mrun += dl;
;             const float alpha = __builtin_amdgcn_exp2f(-dl); lrun *= alpha;
; #pragma unroll
.LBB0_319:
	s_or_b64 exec, exec, s[0:1]
	v_mul_u32_u24_e32 v146, 0xd0, v1
	v_add_f32_e32 v1, 0, v64
	v_add_f32_e32 v1, v65, v1
	v_add_f32_e32 v1, v66, v1
	v_add_f32_e32 v1, v67, v1
	v_add_f32_e32 v1, v68, v1
	v_add_f32_e32 v1, v69, v1
	v_add_f32_e32 v1, v70, v1
	v_add_f32_e32 v1, v71, v1
	v_add_f32_e32 v1, v72, v1
	v_add_f32_e32 v1, v73, v1
	v_add_f32_e32 v1, v74, v1
	v_add_f32_e32 v1, v75, v1
	v_add_f32_e32 v1, v76, v1
	v_add_f32_e32 v1, v77, v1
	v_add_f32_e32 v1, v3, v1
	v_add_f32_e32 v1, v4, v1
	v_add_f32_e32 v1, v5, v1
	v_add_f32_e32 v1, v6, v1
	v_add_f32_e32 v1, v7, v1
	v_add_f32_e32 v1, v8, v1
	v_add_f32_e32 v1, v9, v1
	v_add_f32_e32 v1, v10, v1
	v_add_f32_e32 v1, v11, v1
	v_add_f32_e32 v1, v12, v1
	v_add_f32_e32 v1, v13, v1
	v_add_f32_e32 v1, v14, v1
	v_add_f32_e32 v1, v15, v1
	v_add_f32_e32 v1, v48, v1
	v_add_f32_e32 v1, v49, v1
	v_add_f32_e32 v1, v50, v1
	v_add_f32_e32 v1, v51, v1
	s_cmp_eq_u32 s5, 0
	v_add_f32_e32 v1, v52, v1
	s_cselect_b32 s5, 4, 0x84
	v_ashrrev_i32_e32 v131, 31, v130
	s_add_u32 s0, s30, s28
	v_add_f32_e32 v147, v2, v1
	v_lshlrev_b64 v[2:3], 10, v[130:131]
	s_addc_u32 s1, 0, s29
	v_lshl_add_u64 v[2:3], v[2:3], 0, s[0:1]
	v_lshl_add_u64 v[2:3], v[128:129], 1, v[2:3]
	s_mov_b64 s[8:9], 0x19f30000
	v_lshl_add_u64 v[128:129], v[2:3], 0, s[8:9]
	v_lshlrev_b64 v[2:3], 6, v[130:131]
	v_lshl_add_u64 v[2:3], v[2:3], 0, s[58:59]
	s_waitcnt vmcnt(0)
	ds_write_b128 v123, v[112:115] offset:58368
	v_lshl_add_u64 v[2:3], v[156:157], 1, v[2:3]
	s_mov_b64 s[12:13], 0x1c002f80
	v_ashrrev_i32_e32 v123, 31, v122
	v_lshl_add_u64 v[130:131], v[2:3], 0, s[12:13]
	v_lshlrev_b64 v[2:3], 10, v[122:123]
	v_lshl_add_u64 v[2:3], v[2:3], 0, s[0:1]
	v_lshl_add_u64 v[2:3], v[132:133], 1, v[2:3]
	v_lshl_add_u64 v[132:133], v[2:3], 0, s[8:9]
	v_lshlrev_b64 v[2:3], 6, v[122:123]
	v_lshl_add_u64 v[2:3], v[2:3], 0, s[58:59]
	s_add_u32 s0, s7, 0x1c210180
	v_lshl_add_u64 v[2:3], v[134:135], 1, v[2:3]
	s_addc_u32 s1, 0, 0
	v_and_b32_e32 v1, 7, v136
	v_lshl_add_u64 v[134:135], v[2:3], 0, s[12:13]
	v_lshl_add_u64 v[2:3], s[0:1], 0, v[120:121]
	v_lshlrev_b32_e32 v156, 4, v1
	v_lshl_add_u64 v[2:3], v[2:3], 0, v[156:157]
	s_mov_b32 s6, 1
	v_lshl_add_u64 v[136:137], s[18:19], 1, v[2:3]
	v_mov_b32_e32 v1, v0
	v_mov_b32_e32 v2, v0
	v_mov_b32_e32 v3, v0
	v_mov_b32_e32 v4, v0
	v_mov_b32_e32 v5, v0
	v_mov_b32_e32 v6, v0
	v_mov_b32_e32 v7, v0
	v_mov_b32_e32 v8, v0
	v_mov_b32_e32 v9, v0
	v_mov_b32_e32 v10, v0
	v_mov_b32_e32 v11, v0
	v_mov_b32_e32 v12, v0
	v_mov_b32_e32 v13, v0
	v_mov_b32_e32 v14, v0
	v_mov_b32_e32 v15, v0
	v_mov_b32_e32 v220, 0xf80
	v_mov_b32_e32 v221, 0xff80
	v_cndmask_b32_e64 v222, v130, v128, s[44:45]
	v_cndmask_b32_e64 v223, v134, v132, s[46:47]
	v_cndmask_b32_e64 v130, v220, v221, s[44:45]
	v_cndmask_b32_e64 v134, v220, v221, s[46:47]
	v_mov_b32_e32 v128, v222
	v_cndmask_b32_e64 v132, v222, v223, s[42:43]
	v_cndmask_b32_e64 v134, v130, v134, s[42:43]
	s_mov_b64 s[0:1], s[16:17]
	v_and_b32_e32 v220, 63, v168
	v_mul_u32_u24_e32 v220, 0xd0, v220
	v_add_u32_e32 v220, 0xc0, v220
	v_add_u32_e32 v221, v139, v140
	v_cndmask_b32_e64 v236, v220, v221, s[42:43]
	v_and_b32_e32 v220, 64, v186
	v_xor_b32_e32 v221, 32, v186
	v_add_u32_e32 v220, 64, v220
	v_cmp_lt_i32_e32 vcc, v221, v220
	s_nop 1
	v_cndmask_b32_e32 v221, v186, v221, vcc
	v_lshlrev_b32_e32 v237, 2, v221
	global_load_dwordx4 v[104:107], v128, s[0:1]
	global_load_dwordx4 v[108:111], v132, s[0:1]
	global_load_dwordx4 v[112:115], v136, s[0:1]
	s_add_u32 s0, s0, 0x80
	s_addc_u32 s1, s1, 0
	v_add_u32_e32 v128, v128, v130
	v_add_u32_e32 v132, v132, v134
	s_waitcnt lgkmcnt(0)
	s_movk_i32 s8, 0x5800
	v_add3_u32 v233, s8, v146, v141
	ds_read_b128 v[116:119], v233 offset:0
	ds_read_b128 v[120:123], v233 offset:32
	ds_read_b128 v[148:151], v233 offset:64
	ds_read_b128 v[152:155], v233 offset:96
	v_add3_u32 v232, s8, v143, v141
	s_waitcnt lgkmcnt(2)
	v_mfma_f32_32x32x16_bf16 v[64:79], v[116:119], v[80:83], v[0:15]
	ds_read_b128 v[116:119], v233 offset:128
	v_mfma_f32_32x32x16_bf16 v[64:79], v[120:123], v[84:87], v[64:79]
	ds_read_b128 v[120:123], v233 offset:160
	s_waitcnt lgkmcnt(2)
	v_mfma_f32_32x32x16_bf16 v[64:79], v[148:151], v[88:91], v[64:79]
	ds_read_b128 v[148:151], v233 offset:6656
	v_mfma_f32_32x32x16_bf16 v[64:79], v[152:155], v[92:95], v[64:79]
	ds_read_b128 v[152:155], v233 offset:6688
	s_waitcnt lgkmcnt(2)
	v_mfma_f32_32x32x16_bf16 v[64:79], v[116:119], v[96:99], v[64:79]
	ds_read_b128 v[116:119], v233 offset:6720
	v_mfma_f32_32x32x16_bf16 v[64:79], v[120:123], v[100:103], v[64:79]
	ds_read_b128 v[120:123], v233 offset:6752
	s_waitcnt lgkmcnt(2)
	v_mfma_f32_32x32x16_bf16 v[48:63], v[148:151], v[80:83], v[0:15]
	ds_read_b128 v[148:151], v233 offset:6784
	v_mfma_f32_32x32x16_bf16 v[48:63], v[152:155], v[84:87], v[48:63]
	ds_read_b128 v[152:155], v233 offset:6816
	s_waitcnt lgkmcnt(2)
	v_mfma_f32_32x32x16_bf16 v[48:63], v[116:119], v[88:91], v[48:63]
	v_mfma_f32_32x32x16_bf16 v[48:63], v[120:123], v[92:95], v[48:63]
	s_waitcnt lgkmcnt(0)
	v_mfma_f32_32x32x16_bf16 v[48:63], v[148:151], v[96:99], v[48:63]
	v_mfma_f32_32x32x16_bf16 v[48:63], v[152:155], v[100:103], v[48:63]
	ds_read_b128 v[158:161], v232 offset:13312
	ds_read_b128 v[162:165], v232 offset:17920
	ds_read_b128 v[190:193], v232 offset:13344
	ds_read_b128 v[194:197], v232 offset:17952
	s_nop 15
	v_exp_f32_e32 v216, v64
	v_exp_f32_e32 v217, v65
	v_exp_f32_e32 v218, v66
	v_exp_f32_e32 v219, v67
	v_exp_f32_e32 v220, v68
	v_exp_f32_e32 v221, v69
	v_exp_f32_e32 v222, v70
	v_exp_f32_e32 v223, v71
	v_exp_f32_e32 v224, v72
	v_exp_f32_e32 v225, v73
	v_exp_f32_e32 v226, v74
	v_exp_f32_e32 v227, v75
	v_exp_f32_e32 v228, v76
	v_exp_f32_e32 v229, v77
	v_exp_f32_e32 v230, v78
	v_exp_f32_e32 v231, v79
	s_nop 0
	v_cvt_pk_bf16_f32 v198, v216, v217
	v_cvt_pk_bf16_f32 v199, v218, v219
	v_cvt_pk_bf16_f32 v200, v220, v221
	v_cvt_pk_bf16_f32 v201, v222, v223
	v_cvt_pk_bf16_f32 v208, v224, v225
	v_cvt_pk_bf16_f32 v209, v226, v227
	v_cvt_pk_bf16_f32 v210, v228, v229
	v_cvt_pk_bf16_f32 v211, v230, v231
	s_mov_b32 s18, 0x10800
	s_waitcnt vmcnt(0)
	v_add3_u32 v233, s18, v144, v145
	ds_write_b128 v233, v[104:107] offset:0
	v_add_u32_e32 v233, s18, v236
	ds_write_b128 v233, v[108:111] offset:0
	v_add3_u32 v233, s18, v127, v126
	ds_write_b128 v233, v[112:115] offset:13312
	s_mov_b32 s7, 0x5800
	s_mov_b32 s8, 0xb000
	s_mov_b32 s18, 0x16000
	s_waitcnt lgkmcnt(0)
